# EpiRes epilogues (FF2, out-proj): hoist the 64 x + 16 gate global loads (were each followed by vmcnt(0)) with renamed destinations and counted waits
# speedup vs baseline: 1.0342x; 1.0199x over previous
.LBB0_62:
	s_and_b32 s10, s9, 0x8000
	s_xor_b32 s11, s10, 0x8000
	v_add_u32_e32 v79, s11, v72
	v_lshl_add_u64 v[80:81], v[64:65], 0, s[6:7]
	v_readfirstlane_b32 s11, v79
	v_lshl_add_u64 v[82:83], v[80:81], 0, s[28:29]
	s_mov_b32 m0, s11
	v_lshl_add_u64 v[84:85], v[66:67], 0, s[6:7]
	global_load_lds_dwordx4 v[82:83], off
	v_add_u32_e32 v82, 0x4000, v79
	v_lshl_add_u64 v[86:87], v[84:85], 0, s[28:29]
	v_readfirstlane_b32 s11, v82
	s_mov_b32 m0, s11
	v_lshl_add_u64 v[82:83], v[80:81], 0, s[12:13]
	global_load_lds_dwordx4 v[86:87], off
	v_add_u32_e32 v86, 0x1000, v79
	s_nop 0
	v_readfirstlane_b32 s11, v86
	v_add_u32_e32 v86, 0x5000, v79
	s_mov_b32 m0, s11
	v_readfirstlane_b32 s11, v86
	v_add_u32_e32 v86, 0x2000, v79
	global_load_lds_dwordx4 v[82:83], off
	v_lshl_add_u64 v[82:83], v[84:85], 0, s[12:13]
	s_mov_b32 m0, s11
	v_readfirstlane_b32 s11, v86
	v_add_u32_e32 v86, 0x6000, v79
	global_load_lds_dwordx4 v[82:83], off
	v_lshl_add_u64 v[82:83], v[80:81], 0, s[14:15]
	s_mov_b32 m0, s11
	v_readfirstlane_b32 s11, v86
	global_load_lds_dwordx4 v[82:83], off
	v_lshl_add_u64 v[82:83], v[84:85], 0, s[14:15]
	s_mov_b32 m0, s11
	v_lshl_add_u64 v[80:81], v[80:81], 0, s[16:17]
	global_load_lds_dwordx4 v[82:83], off
	v_add_u32_e32 v82, 0x3000, v79
	v_add_u32_e32 v79, 0x7000, v79
	v_readfirstlane_b32 s11, v82
	s_mov_b32 m0, s11
	v_readfirstlane_b32 s11, v79
	global_load_lds_dwordx4 v[80:81], off
	v_lshl_add_u64 v[80:81], v[84:85], 0, s[16:17]
	s_mov_b32 m0, s11
	v_or_b32_e32 v79, s10, v78
	global_load_lds_dwordx4 v[80:81], off
	v_add_u32_e32 v100, v79, v73
	v_add_u32_e32 v79, v79, v74
	ds_read_b128 v[80:83], v100
	ds_read_b128 v[84:87], v100 offset:2048
	ds_read_b128 v[88:91], v79 offset:16384
	ds_read_b128 v[92:95], v79 offset:18432
	ds_read_b128 v[96:99], v100 offset:4096
	ds_read_b128 v[100:103], v100 offset:6144
	ds_read_b128 v[104:107], v79 offset:20480
	ds_read_b128 v[108:111], v79 offset:22528
	v_or_b32_e32 v79, s10, v77
	v_add_u32_e32 v132, v79, v73
	v_add_u32_e32 v79, v79, v74
	ds_read_b128 v[112:115], v132
	ds_read_b128 v[116:119], v132 offset:2048
	ds_read_b128 v[120:123], v79 offset:16384
	ds_read_b128 v[124:127], v79 offset:18432
	ds_read_b128 v[128:131], v132 offset:4096
	ds_read_b128 v[132:135], v132 offset:6144
	ds_read_b128 v[146:149], v79 offset:20480
	ds_read_b128 v[150:153], v79 offset:22528
	s_waitcnt lgkmcnt(0)
	v_mfma_f32_16x16x32_bf16 v[60:63], v[80:83], v[88:91], v[60:63]
	v_mfma_f32_16x16x32_bf16 v[56:59], v[80:83], v[92:95], v[56:59]
	v_mfma_f32_16x16x32_bf16 v[52:55], v[80:83], v[104:107], v[52:55]
	v_mfma_f32_16x16x32_bf16 v[48:51], v[80:83], v[108:111], v[48:51]
	v_mfma_f32_16x16x32_bf16 v[44:47], v[84:87], v[88:91], v[44:47]
	v_mfma_f32_16x16x32_bf16 v[40:43], v[84:87], v[92:95], v[40:43]
	v_mfma_f32_16x16x32_bf16 v[36:39], v[84:87], v[104:107], v[36:39]
	v_mfma_f32_16x16x32_bf16 v[32:35], v[84:87], v[108:111], v[32:35]
	v_mfma_f32_16x16x32_bf16 v[28:31], v[96:99], v[88:91], v[28:31]
	v_mfma_f32_16x16x32_bf16 v[24:27], v[96:99], v[92:95], v[24:27]
	v_mfma_f32_16x16x32_bf16 v[20:23], v[96:99], v[104:107], v[20:23]
	v_mfma_f32_16x16x32_bf16 v[16:19], v[96:99], v[108:111], v[16:19]
	v_mfma_f32_16x16x32_bf16 v[12:15], v[100:103], v[88:91], v[12:15]
	v_mfma_f32_16x16x32_bf16 v[8:11], v[100:103], v[92:95], v[8:11]
	v_mfma_f32_16x16x32_bf16 v[4:7], v[100:103], v[104:107], v[4:7]
	v_mfma_f32_16x16x32_bf16 v[0:3], v[100:103], v[108:111], v[0:3]
	v_mfma_f32_16x16x32_bf16 v[60:63], v[112:115], v[120:123], v[60:63]
	v_mfma_f32_16x16x32_bf16 v[56:59], v[112:115], v[124:127], v[56:59]
	v_mfma_f32_16x16x32_bf16 v[52:55], v[112:115], v[146:149], v[52:55]
	v_mfma_f32_16x16x32_bf16 v[48:51], v[112:115], v[150:153], v[48:51]
	v_mfma_f32_16x16x32_bf16 v[44:47], v[116:119], v[120:123], v[44:47]
	v_mfma_f32_16x16x32_bf16 v[40:43], v[116:119], v[124:127], v[40:43]
	v_mfma_f32_16x16x32_bf16 v[36:39], v[116:119], v[146:149], v[36:39]
	v_mfma_f32_16x16x32_bf16 v[32:35], v[116:119], v[150:153], v[32:35]
	v_mfma_f32_16x16x32_bf16 v[28:31], v[128:131], v[120:123], v[28:31]
	v_mfma_f32_16x16x32_bf16 v[24:27], v[128:131], v[124:127], v[24:27]
	v_mfma_f32_16x16x32_bf16 v[20:23], v[128:131], v[146:149], v[20:23]
	v_mfma_f32_16x16x32_bf16 v[16:19], v[128:131], v[150:153], v[16:19]
	v_mfma_f32_16x16x32_bf16 v[12:15], v[132:135], v[120:123], v[12:15]
	v_mfma_f32_16x16x32_bf16 v[8:11], v[132:135], v[124:127], v[8:11]
	v_mfma_f32_16x16x32_bf16 v[4:7], v[132:135], v[146:149], v[4:7]
	v_mfma_f32_16x16x32_bf16 v[0:3], v[132:135], v[150:153], v[0:3]
	s_waitcnt vmcnt(0)
	s_add_u32 s6, s6, 0x80
	s_addc_u32 s7, s7, 0
	s_add_i32 s9, s9, 0x8000
	s_cmpk_eq_i32 s6, 0x1f80
	s_barrier
	s_cbranch_scc0 .LBB0_62
	v_add_u32_e32 v72, v78, v73
	v_add_u32_e32 v102, v78, v74
	ds_read_b128 v[64:67], v72 offset:32768
	ds_read_b128 v[78:81], v72 offset:34816
	ds_read_b128 v[82:85], v102 offset:49152
	ds_read_b128 v[86:89], v102 offset:51200
	ds_read_b128 v[90:93], v72 offset:36864
	ds_read_b128 v[94:97], v72 offset:38912
	ds_read_b128 v[98:101], v102 offset:53248
	ds_read_b128 v[102:105], v102 offset:55296
	v_add_u32_e32 v72, v77, v73
	v_add_u32_e32 v73, v77, v74
	ds_read_b128 v[106:109], v72 offset:32768
	ds_read_b128 v[110:113], v72 offset:34816
	ds_read_b128 v[114:117], v73 offset:49152
	ds_read_b128 v[118:121], v73 offset:51200
	ds_read_b128 v[122:125], v72 offset:36864
	ds_read_b128 v[126:129], v72 offset:38912
	ds_read_b128 v[130:133], v73 offset:53248
	ds_read_b128 v[146:149], v73 offset:55296
	s_waitcnt lgkmcnt(13)
	v_mfma_f32_16x16x32_bf16 v[60:63], v[64:67], v[82:85], v[60:63]
	s_waitcnt lgkmcnt(12)
	v_mfma_f32_16x16x32_bf16 v[56:59], v[64:67], v[86:89], v[56:59]
	s_waitcnt lgkmcnt(9)
	v_mfma_f32_16x16x32_bf16 v[52:55], v[64:67], v[98:101], v[52:55]
	s_waitcnt lgkmcnt(8)
	v_mfma_f32_16x16x32_bf16 v[48:51], v[64:67], v[102:105], v[48:51]
	v_mfma_f32_16x16x32_bf16 v[44:47], v[78:81], v[82:85], v[44:47]
	v_mfma_f32_16x16x32_bf16 v[40:43], v[78:81], v[86:89], v[40:43]
	v_mfma_f32_16x16x32_bf16 v[36:39], v[78:81], v[98:101], v[36:39]
	v_mfma_f32_16x16x32_bf16 v[32:35], v[78:81], v[102:105], v[32:35]
	v_mfma_f32_16x16x32_bf16 v[28:31], v[90:93], v[82:85], v[28:31]
	v_mfma_f32_16x16x32_bf16 v[24:27], v[90:93], v[86:89], v[24:27]
	v_mfma_f32_16x16x32_bf16 v[20:23], v[90:93], v[98:101], v[20:23]
	v_mfma_f32_16x16x32_bf16 v[16:19], v[90:93], v[102:105], v[16:19]
	v_mfma_f32_16x16x32_bf16 v[12:15], v[94:97], v[82:85], v[12:15]
	v_mfma_f32_16x16x32_bf16 v[8:11], v[94:97], v[86:89], v[8:11]
	v_mfma_f32_16x16x32_bf16 v[4:7], v[94:97], v[98:101], v[4:7]
	v_mfma_f32_16x16x32_bf16 v[0:3], v[94:97], v[102:105], v[0:3]
	s_waitcnt lgkmcnt(5)
	v_mfma_f32_16x16x32_bf16 v[78:81], v[106:109], v[114:117], v[60:63]
	s_waitcnt lgkmcnt(4)
	v_mfma_f32_16x16x32_bf16 v[56:59], v[106:109], v[118:121], v[56:59]
	s_waitcnt lgkmcnt(1)
	v_mfma_f32_16x16x32_bf16 v[52:55], v[106:109], v[130:133], v[52:55]
	s_waitcnt lgkmcnt(0)
	v_mfma_f32_16x16x32_bf16 v[48:51], v[106:109], v[146:149], v[48:51]
	v_mfma_f32_16x16x32_bf16 v[44:47], v[110:113], v[114:117], v[44:47]
	v_mfma_f32_16x16x32_bf16 v[40:43], v[110:113], v[118:121], v[40:43]
	v_mfma_f32_16x16x32_bf16 v[36:39], v[110:113], v[130:133], v[36:39]
	v_mfma_f32_16x16x32_bf16 v[32:35], v[110:113], v[146:149], v[32:35]
	v_mfma_f32_16x16x32_bf16 v[28:31], v[122:125], v[114:117], v[28:31]
	v_mfma_f32_16x16x32_bf16 v[24:27], v[122:125], v[118:121], v[24:27]
	v_mfma_f32_16x16x32_bf16 v[20:23], v[122:125], v[130:133], v[20:23]
	v_mfma_f32_16x16x32_bf16 v[16:19], v[122:125], v[146:149], v[16:19]
	v_mfma_f32_16x16x32_bf16 v[12:15], v[126:129], v[114:117], v[12:15]
	v_mfma_f32_16x16x32_bf16 v[8:11], v[126:129], v[118:121], v[8:11]
	v_mfma_f32_16x16x32_bf16 v[4:7], v[126:129], v[130:133], v[4:7]
	v_mfma_f32_16x16x32_bf16 v[0:3], v[126:129], v[146:149], v[0:3]
	v_add_u32_e32 v72, s5, v69
	v_add_u32_e32 v61, 0xfffff000, v72
	s_movk_i32 s6, 0x2400
	v_lshl_or_b32 v60, v75, 2, v72
	v_lshrrev_b32_e32 v61, 12, v61
	s_movk_i32 s9, 0xfff
	v_mul_lo_u32 v74, v68, s6
	v_add_u32_e32 v61, 1, v61
	v_cmp_lt_i32_e32 vcc, s9, v60
	v_readlane_b32 s6, v245, 34
	v_readlane_b32 s7, v245, 35
	v_cndmask_b32_e32 v136, 0, v61, vcc
	v_lshl_add_u64 v[66:67], v[136:137], 0, s[0:1]
	v_mov_b64_e32 v[64:65], s[6:7]
	s_movk_i32 s5, 0x6000
	v_mad_u64_u32 v[68:69], s[6:7], v66, s5, v[64:65]
	v_or_b32_e32 v66, 1, v60
	v_mad_i32_i24 v69, v67, s5, v69
	v_ashrrev_i32_e32 v67, 31, v66
	v_lshlrev_b64 v[84:85], 12, v[66:67]
	v_or_b32_e32 v66, 2, v60
	v_and_b32_e32 v73, 64, v71
	v_ashrrev_i32_e32 v67, 31, v66
	v_or3_b32 v62, v76, s4, v73
	v_lshlrev_b64 v[86:87], 12, v[66:67]
	v_or_b32_e32 v66, 3, v60
	v_readlane_b32 s36, v247, 57
	v_ashrrev_i32_e32 v61, 31, v60
	v_ashrrev_i32_e32 v67, 31, v66
	v_ashrrev_i32_e32 v63, 31, v62
	v_readlane_b32 s46, v246, 3
	v_readlane_b32 s47, v246, 4
	v_lshlrev_b64 v[82:83], 12, v[60:61]
	v_lshlrev_b64 v[88:89], 12, v[66:67]
	v_lshlrev_b64 v[66:67], 2, v[62:63]
	v_lshl_add_u64 v[62:63], v[62:63], 1, s[46:47]
	v_lshl_add_u64 v[82:83], v[62:63], 0, v[82:83]
	s_waitcnt vmcnt(0)
	s_barrier
	global_load_ushort v202, v[82:83], off
	v_lshl_add_u64 v[68:69], v[68:69], 0, v[66:67]
	global_load_dword v203, v[68:69], off
	v_lshl_add_u64 v[84:85], v[62:63], 0, v[84:85]
	global_load_ushort v204, v[84:85], off
	s_movk_i32 s6, 0x240
	s_movk_i32 s36, 0x880
	v_readlane_b32 s37, v247, 58
	v_readlane_b32 s38, v247, 59
	v_readlane_b32 s39, v247, 60
	v_readlane_b32 s40, v247, 61
	v_readlane_b32 s41, v247, 62
	v_readlane_b32 s42, v247, 63
	v_readlane_b32 s43, v246, 0
	v_readlane_b32 s44, v246, 1
	v_readlane_b32 s45, v246, 2
	v_readlane_b32 s48, v246, 5
	v_readlane_b32 s49, v246, 6
	v_readlane_b32 s50, v246, 7
	v_readlane_b32 s51, v246, 8
	s_waitcnt vmcnt(2)
	v_lshlrev_b32_e32 v77, 16, v202
	v_mul_f32_e32 v77, 0x3fd744fd, v77
	s_waitcnt vmcnt(1)
	v_fmac_f32_e32 v77, v78, v203
	s_waitcnt vmcnt(0)
	v_lshlrev_b32_e32 v78, 16, v204
	v_mul_f32_e32 v90, 0x3fd744fd, v78
	v_fmac_f32_e32 v90, v79, v203
	v_lshl_add_u64 v[78:79], v[62:63], 0, v[86:87]
	global_load_ushort v205, v[78:79], off
	s_waitcnt vmcnt(0)
	v_lshlrev_b32_e32 v86, 16, v205
	v_mul_f32_e32 v91, 0x3fd744fd, v86
	v_lshl_add_u64 v[86:87], v[62:63], 0, v[88:89]
	global_load_ushort v206, v[86:87], off
	global_load_dword v207, v[68:69], off offset:64
	global_load_ushort v208, v[82:83], off offset:32
	global_load_ushort v209, v[84:85], off offset:32
	global_load_ushort v210, v[78:79], off offset:32
	global_load_ushort v211, v[86:87], off offset:32
	global_load_dword v212, v[68:69], off offset:128
	global_load_ushort v213, v[82:83], off offset:64
	global_load_ushort v214, v[84:85], off offset:64
	global_load_ushort v215, v[78:79], off offset:64
	global_load_ushort v216, v[86:87], off offset:64
	global_load_dword v217, v[68:69], off offset:192
	global_load_ushort v218, v[82:83], off offset:96
	global_load_ushort v219, v[84:85], off offset:96
	global_load_ushort v220, v[78:79], off offset:96
	global_load_ushort v221, v[86:87], off offset:96
	v_fmac_f32_e32 v91, v80, v203
	s_waitcnt vmcnt(15)
	v_lshlrev_b32_e32 v80, 16, v206
	v_mul_f32_e32 v80, 0x3fd744fd, v80
	v_fmac_f32_e32 v80, v81, v203
	v_lshl_or_b32 v61, v76, 1, v74
	v_mad_u32_u24 v61, v75, s6, v61
	v_cvt_pk_bf16_f32 v75, v90, s0
	ds_write_b16 v61, v75 offset:144
	v_cvt_pk_bf16_f32 v75, v91, s0
	v_cvt_pk_bf16_f32 v76, v77, s0
	ds_write_b16 v61, v75 offset:288
	v_cvt_pk_bf16_f32 v75, v80, s0
	ds_write_b16 v61, v76
	ds_write_b16 v61, v75 offset:432
	s_waitcnt vmcnt(13)
	v_lshlrev_b32_e32 v76, 16, v208
	v_mul_f32_e32 v76, 0x3fd744fd, v76
	v_fmac_f32_e32 v76, v56, v207
	s_waitcnt vmcnt(12)
	v_lshlrev_b32_e32 v56, 16, v209
	v_mul_f32_e32 v56, 0x3fd744fd, v56
	v_fmac_f32_e32 v56, v57, v207
	v_cvt_pk_bf16_f32 v56, v56, s0
	ds_write_b16 v61, v56 offset:176
	s_waitcnt vmcnt(11)
	v_lshlrev_b32_e32 v57, 16, v210
	v_mul_f32_e32 v57, 0x3fd744fd, v57
	v_fmac_f32_e32 v57, v58, v207
	v_cvt_pk_bf16_f32 v56, v57, s0
	ds_write_b16 v61, v56 offset:320
	s_waitcnt vmcnt(10)
	v_lshlrev_b32_e32 v58, 16, v211
	v_mul_f32_e32 v58, 0x3fd744fd, v58
	v_fmac_f32_e32 v58, v59, v207
	v_cvt_pk_bf16_f32 v59, v76, s0
	v_cvt_pk_bf16_f32 v56, v58, s0
	ds_write_b16 v61, v59 offset:32
	ds_write_b16 v61, v56 offset:464
	s_waitcnt vmcnt(8)
	v_lshlrev_b32_e32 v57, 16, v213
	v_mul_f32_e32 v57, 0x3fd744fd, v57
	v_fmac_f32_e32 v57, v52, v212
	s_waitcnt vmcnt(7)
	v_lshlrev_b32_e32 v52, 16, v214
	v_mul_f32_e32 v52, 0x3fd744fd, v52
	v_fmac_f32_e32 v52, v53, v212
	v_cvt_pk_bf16_f32 v52, v52, s0
	ds_write_b16 v61, v52 offset:208
	s_waitcnt vmcnt(6)
	v_lshlrev_b32_e32 v53, 16, v215
	v_mul_f32_e32 v53, 0x3fd744fd, v53
	v_fmac_f32_e32 v53, v54, v212
	v_cvt_pk_bf16_f32 v52, v53, s0
	ds_write_b16 v61, v52 offset:352
	s_waitcnt vmcnt(5)
	v_lshlrev_b32_e32 v54, 16, v216
	v_mul_f32_e32 v54, 0x3fd744fd, v54
	v_fmac_f32_e32 v54, v55, v212
	v_cvt_pk_bf16_f32 v55, v57, s0
	v_cvt_pk_bf16_f32 v52, v54, s0
	ds_write_b16 v61, v55 offset:64
	ds_write_b16 v61, v52 offset:496
	v_or_b32_e32 v54, 18, v60
	v_ashrrev_i32_e32 v55, 31, v54
	v_lshlrev_b64 v[56:57], 12, v[54:55]
	v_or_b32_e32 v54, 19, v60
	v_ashrrev_i32_e32 v55, 31, v54
	v_lshlrev_b64 v[58:59], 12, v[54:55]
	s_waitcnt vmcnt(3)
	v_lshlrev_b32_e32 v53, 16, v218
	v_mul_f32_e32 v53, 0x3fd744fd, v53
	v_fmac_f32_e32 v53, v48, v217
	s_waitcnt vmcnt(2)
	v_lshlrev_b32_e32 v48, 16, v219
	v_mul_f32_e32 v48, 0x3fd744fd, v48
	v_fmac_f32_e32 v48, v49, v217
	v_cvt_pk_bf16_f32 v48, v48, s0
	ds_write_b16 v61, v48 offset:240
	s_waitcnt vmcnt(1)
	v_lshlrev_b32_e32 v49, 16, v220
	v_mul_f32_e32 v49, 0x3fd744fd, v49
	v_fmac_f32_e32 v49, v50, v217
	v_cvt_pk_bf16_f32 v48, v49, s0
	ds_write_b16 v61, v48 offset:384
	v_add_u32_e32 v49, 0xfffff010, v72
	v_lshrrev_b32_e32 v49, 12, v49
	v_add_u32_e32 v49, 1, v49
	s_waitcnt vmcnt(0)
	v_lshlrev_b32_e32 v50, 16, v221
	v_mul_f32_e32 v50, 0x3fd744fd, v50
	v_fmac_f32_e32 v50, v51, v217
	v_cvt_pk_bf16_f32 v48, v50, s0
	ds_write_b16 v61, v48 offset:528
	v_or_b32_e32 v48, 16, v60
	v_cmp_lt_i32_e32 vcc, s9, v48
	v_cvt_pk_bf16_f32 v51, v53, s0
	ds_write_b16 v61, v51 offset:96
	v_cndmask_b32_e32 v136, 0, v49, vcc
	v_ashrrev_i32_e32 v49, 31, v48
	v_lshl_add_u64 v[50:51], v[136:137], 0, s[0:1]
	v_lshlrev_b64 v[48:49], 12, v[48:49]
	v_mad_u64_u32 v[52:53], s[6:7], v50, s5, v[64:65]
	v_lshl_add_u64 v[54:55], v[62:63], 0, v[48:49]
	global_load_ushort v222, v[54:55], off
	v_mad_i32_i24 v53, v51, s5, v53
	v_lshl_add_u64 v[52:53], v[52:53], 0, v[66:67]
	global_load_dword v223, v[52:53], off
	v_or_b32_e32 v50, 17, v60
	v_ashrrev_i32_e32 v51, 31, v50
	v_lshlrev_b64 v[50:51], 12, v[50:51]
	s_waitcnt vmcnt(1)
	v_lshlrev_b32_e32 v48, 16, v222
	v_mul_f32_e32 v69, 0x3fd744fd, v48
	v_lshl_add_u64 v[48:49], v[62:63], 0, v[50:51]
	global_load_ushort v224, v[48:49], off
	s_waitcnt vmcnt(1)
	v_fmac_f32_e32 v69, v44, v223
	v_lshl_add_u64 v[50:51], v[62:63], 0, v[56:57]
	global_load_ushort v225, v[50:51], off
	s_waitcnt vmcnt(1)
	v_lshlrev_b32_e32 v44, 16, v224
	v_mul_f32_e32 v75, 0x3fd744fd, v44
	v_fmac_f32_e32 v75, v45, v223
	s_waitcnt vmcnt(0)
	v_lshlrev_b32_e32 v44, 16, v225
	v_mul_f32_e32 v56, 0x3fd744fd, v44
	v_lshl_add_u64 v[44:45], v[62:63], 0, v[58:59]
	global_load_ushort v226, v[44:45], off
	global_load_dword v227, v[52:53], off offset:64
	global_load_ushort v228, v[54:55], off offset:32
	global_load_ushort v229, v[48:49], off offset:32
	global_load_ushort v230, v[50:51], off offset:32
	global_load_ushort v231, v[44:45], off offset:32
	global_load_dword v232, v[52:53], off offset:128
	global_load_ushort v233, v[54:55], off offset:64
	global_load_ushort v234, v[48:49], off offset:64
	global_load_ushort v235, v[50:51], off offset:64
	global_load_ushort v236, v[44:45], off offset:64
	global_load_dword v237, v[52:53], off offset:192
	global_load_ushort v238, v[54:55], off offset:96
	global_load_ushort v239, v[48:49], off offset:96
	global_load_ushort v240, v[50:51], off offset:96
	global_load_ushort v241, v[44:45], off offset:96
	v_fmac_f32_e32 v56, v46, v223
	s_waitcnt vmcnt(15)
	v_lshlrev_b32_e32 v46, 16, v226
	v_mul_f32_e32 v46, 0x3fd744fd, v46
	v_fmac_f32_e32 v46, v47, v223
	v_cvt_pk_bf16_f32 v47, v69, s0
	ds_write_b16 v61, v47 offset:2304
	v_cvt_pk_bf16_f32 v47, v75, s0
	ds_write_b16 v61, v47 offset:2448
	v_cvt_pk_bf16_f32 v47, v56, s0
	v_cvt_pk_bf16_f32 v46, v46, s0
	ds_write_b16 v61, v47 offset:2592
	ds_write_b16 v61, v46 offset:2736
	s_waitcnt vmcnt(13)
	v_lshlrev_b32_e32 v47, 16, v228
	v_mul_f32_e32 v47, 0x3fd744fd, v47
	v_fmac_f32_e32 v47, v40, v227
	s_waitcnt vmcnt(12)
	v_lshlrev_b32_e32 v40, 16, v229
	v_mul_f32_e32 v40, 0x3fd744fd, v40
	v_fmac_f32_e32 v40, v41, v227
	v_cvt_pk_bf16_f32 v40, v40, s0
	ds_write_b16 v61, v40 offset:2480
	s_waitcnt vmcnt(11)
	v_lshlrev_b32_e32 v41, 16, v230
	v_mul_f32_e32 v41, 0x3fd744fd, v41
	v_fmac_f32_e32 v41, v42, v227
	v_cvt_pk_bf16_f32 v40, v41, s0
	ds_write_b16 v61, v40 offset:2624
	s_waitcnt vmcnt(10)
	v_lshlrev_b32_e32 v42, 16, v231
	v_mul_f32_e32 v42, 0x3fd744fd, v42
	v_fmac_f32_e32 v42, v43, v227
	v_cvt_pk_bf16_f32 v43, v47, s0
	v_cvt_pk_bf16_f32 v40, v42, s0
	ds_write_b16 v61, v43 offset:2336
	ds_write_b16 v61, v40 offset:2768
	s_waitcnt vmcnt(8)
	v_lshlrev_b32_e32 v41, 16, v233
	v_mul_f32_e32 v41, 0x3fd744fd, v41
	v_fmac_f32_e32 v41, v36, v232
	s_waitcnt vmcnt(7)
	v_lshlrev_b32_e32 v36, 16, v234
	v_mul_f32_e32 v36, 0x3fd744fd, v36
	v_fmac_f32_e32 v36, v37, v232
	v_cvt_pk_bf16_f32 v36, v36, s0
	ds_write_b16 v61, v36 offset:2512
	s_waitcnt vmcnt(6)
	v_lshlrev_b32_e32 v37, 16, v235
	v_mul_f32_e32 v37, 0x3fd744fd, v37
	v_fmac_f32_e32 v37, v38, v232
	v_cvt_pk_bf16_f32 v36, v37, s0
	ds_write_b16 v61, v36 offset:2656
	s_waitcnt vmcnt(5)
	v_lshlrev_b32_e32 v38, 16, v236
	v_mul_f32_e32 v38, 0x3fd744fd, v38
	v_fmac_f32_e32 v38, v39, v232
	v_cvt_pk_bf16_f32 v39, v41, s0
	v_cvt_pk_bf16_f32 v36, v38, s0
	ds_write_b16 v61, v39 offset:2368
	ds_write_b16 v61, v36 offset:2800
	v_or_b32_e32 v38, 34, v60
	v_ashrrev_i32_e32 v39, 31, v38
	v_lshlrev_b64 v[40:41], 12, v[38:39]
	v_or_b32_e32 v38, 35, v60
	v_ashrrev_i32_e32 v39, 31, v38
	v_lshlrev_b64 v[42:43], 12, v[38:39]
	s_waitcnt vmcnt(3)
	v_lshlrev_b32_e32 v37, 16, v238
	v_mul_f32_e32 v37, 0x3fd744fd, v37
	v_fmac_f32_e32 v37, v32, v237
	s_waitcnt vmcnt(2)
	v_lshlrev_b32_e32 v32, 16, v239
	v_mul_f32_e32 v32, 0x3fd744fd, v32
	v_fmac_f32_e32 v32, v33, v237
	v_cvt_pk_bf16_f32 v32, v32, s0
	ds_write_b16 v61, v32 offset:2544
	s_waitcnt vmcnt(1)
	v_lshlrev_b32_e32 v33, 16, v240
	v_mul_f32_e32 v33, 0x3fd744fd, v33
	v_fmac_f32_e32 v33, v34, v237
	v_cvt_pk_bf16_f32 v32, v33, s0
	ds_write_b16 v61, v32 offset:2688
	v_add_u32_e32 v33, 0xfffff020, v72
	v_lshrrev_b32_e32 v33, 12, v33
	v_add_u32_e32 v33, 1, v33
	s_waitcnt vmcnt(0)
	v_lshlrev_b32_e32 v34, 16, v241
	v_mul_f32_e32 v34, 0x3fd744fd, v34
	v_fmac_f32_e32 v34, v35, v237
	v_cvt_pk_bf16_f32 v32, v34, s0
	ds_write_b16 v61, v32 offset:2832
	v_or_b32_e32 v32, 32, v60
	v_cmp_lt_i32_e32 vcc, s9, v32
	v_cvt_pk_bf16_f32 v35, v37, s0
	ds_write_b16 v61, v35 offset:2400
	v_cndmask_b32_e32 v136, 0, v33, vcc
	v_ashrrev_i32_e32 v33, 31, v32
	v_lshl_add_u64 v[34:35], v[136:137], 0, s[0:1]
	v_lshlrev_b64 v[32:33], 12, v[32:33]
	v_mad_u64_u32 v[36:37], s[6:7], v34, s5, v[64:65]
	v_lshl_add_u64 v[38:39], v[62:63], 0, v[32:33]
	global_load_ushort v248, v[38:39], off
	v_mad_i32_i24 v37, v35, s5, v37
	v_lshl_add_u64 v[36:37], v[36:37], 0, v[66:67]
	global_load_dword v249, v[36:37], off
	v_or_b32_e32 v34, 33, v60
	v_ashrrev_i32_e32 v35, 31, v34
	v_lshlrev_b64 v[34:35], 12, v[34:35]
	s_waitcnt vmcnt(1)
	v_lshlrev_b32_e32 v32, 16, v248
	v_mul_f32_e32 v45, 0x3fd744fd, v32
	v_lshl_add_u64 v[32:33], v[62:63], 0, v[34:35]
	global_load_ushort v250, v[32:33], off
	s_waitcnt vmcnt(1)
	v_fmac_f32_e32 v45, v28, v249
	v_lshl_add_u64 v[34:35], v[62:63], 0, v[40:41]
	global_load_ushort v251, v[34:35], off
	s_waitcnt vmcnt(1)
	v_lshlrev_b32_e32 v28, 16, v250
	v_mul_f32_e32 v46, 0x3fd744fd, v28
	v_fmac_f32_e32 v46, v29, v249
	s_waitcnt vmcnt(0)
	v_lshlrev_b32_e32 v28, 16, v251
	v_mul_f32_e32 v40, 0x3fd744fd, v28
	v_lshl_add_u64 v[28:29], v[62:63], 0, v[42:43]
	global_load_ushort v252, v[28:29], off
	global_load_dword v253, v[36:37], off offset:64
	global_load_ushort v254, v[38:39], off offset:32
	global_load_ushort v255, v[32:33], off offset:32
	global_load_ushort v202, v[34:35], off offset:32
	global_load_ushort v203, v[28:29], off offset:32
	global_load_dword v204, v[36:37], off offset:128
	global_load_ushort v205, v[38:39], off offset:64
	global_load_ushort v206, v[32:33], off offset:64
	global_load_ushort v207, v[34:35], off offset:64
	global_load_ushort v208, v[28:29], off offset:64
	global_load_dword v209, v[36:37], off offset:192
	global_load_ushort v210, v[38:39], off offset:96
	global_load_ushort v211, v[32:33], off offset:96
	global_load_ushort v212, v[34:35], off offset:96
	global_load_ushort v213, v[28:29], off offset:96
	v_fmac_f32_e32 v40, v30, v249
	s_waitcnt vmcnt(15)
	v_lshlrev_b32_e32 v30, 16, v252
	v_mul_f32_e32 v30, 0x3fd744fd, v30
	v_fmac_f32_e32 v30, v31, v249
	v_cvt_pk_bf16_f32 v31, v45, s0
	ds_write_b16 v61, v31 offset:4608
	v_cvt_pk_bf16_f32 v31, v46, s0
	ds_write_b16 v61, v31 offset:4752
	v_cvt_pk_bf16_f32 v31, v40, s0
	v_cvt_pk_bf16_f32 v30, v30, s0
	ds_write_b16 v61, v31 offset:4896
	ds_write_b16 v61, v30 offset:5040
	s_waitcnt vmcnt(13)
	v_lshlrev_b32_e32 v31, 16, v254
	v_mul_f32_e32 v31, 0x3fd744fd, v31
	v_fmac_f32_e32 v31, v24, v253
	s_waitcnt vmcnt(12)
	v_lshlrev_b32_e32 v24, 16, v255
	v_mul_f32_e32 v24, 0x3fd744fd, v24
	v_fmac_f32_e32 v24, v25, v253
	v_cvt_pk_bf16_f32 v24, v24, s0
	ds_write_b16 v61, v24 offset:4784
	s_waitcnt vmcnt(11)
	v_lshlrev_b32_e32 v25, 16, v202
	v_mul_f32_e32 v25, 0x3fd744fd, v25
	v_fmac_f32_e32 v25, v26, v253
	v_cvt_pk_bf16_f32 v24, v25, s0
	ds_write_b16 v61, v24 offset:4928
	s_waitcnt vmcnt(10)
	v_lshlrev_b32_e32 v26, 16, v203
	v_mul_f32_e32 v26, 0x3fd744fd, v26
	v_fmac_f32_e32 v26, v27, v253
	v_cvt_pk_bf16_f32 v27, v31, s0
	v_cvt_pk_bf16_f32 v24, v26, s0
	ds_write_b16 v61, v27 offset:4640
	ds_write_b16 v61, v24 offset:5072
	s_waitcnt vmcnt(8)
	v_lshlrev_b32_e32 v25, 16, v205
	v_mul_f32_e32 v25, 0x3fd744fd, v25
	v_fmac_f32_e32 v25, v20, v204
	s_waitcnt vmcnt(7)
	v_lshlrev_b32_e32 v20, 16, v206
	v_mul_f32_e32 v20, 0x3fd744fd, v20
	v_fmac_f32_e32 v20, v21, v204
	v_cvt_pk_bf16_f32 v20, v20, s0
	ds_write_b16 v61, v20 offset:4816
	s_waitcnt vmcnt(6)
	v_lshlrev_b32_e32 v21, 16, v207
	v_mul_f32_e32 v21, 0x3fd744fd, v21
	v_fmac_f32_e32 v21, v22, v204
	v_cvt_pk_bf16_f32 v20, v21, s0
	ds_write_b16 v61, v20 offset:4960
	s_waitcnt vmcnt(5)
	v_lshlrev_b32_e32 v22, 16, v208
	v_mul_f32_e32 v22, 0x3fd744fd, v22
	v_fmac_f32_e32 v22, v23, v204
	v_cvt_pk_bf16_f32 v23, v25, s0
	v_cvt_pk_bf16_f32 v20, v22, s0
	ds_write_b16 v61, v23 offset:4672
	ds_write_b16 v61, v20 offset:5104
	v_or_b32_e32 v22, 50, v60
	v_ashrrev_i32_e32 v23, 31, v22
	v_lshlrev_b64 v[24:25], 12, v[22:23]
	v_or_b32_e32 v22, 51, v60
	v_ashrrev_i32_e32 v23, 31, v22
	v_lshlrev_b64 v[26:27], 12, v[22:23]
	s_waitcnt vmcnt(3)
	v_lshlrev_b32_e32 v21, 16, v210
	v_mul_f32_e32 v21, 0x3fd744fd, v21
	v_fmac_f32_e32 v21, v16, v209
	s_waitcnt vmcnt(2)
	v_lshlrev_b32_e32 v16, 16, v211
	v_mul_f32_e32 v16, 0x3fd744fd, v16
	v_fmac_f32_e32 v16, v17, v209
	v_cvt_pk_bf16_f32 v16, v16, s0
	ds_write_b16 v61, v16 offset:4848
	s_waitcnt vmcnt(1)
	v_lshlrev_b32_e32 v17, 16, v212
	v_mul_f32_e32 v17, 0x3fd744fd, v17
	v_fmac_f32_e32 v17, v18, v209
	v_cvt_pk_bf16_f32 v16, v17, s0
	ds_write_b16 v61, v16 offset:4992
	v_add_u32_e32 v17, 0xfffff030, v72
	v_lshrrev_b32_e32 v17, 12, v17
	v_add_u32_e32 v17, 1, v17
	s_waitcnt vmcnt(0)
	v_lshlrev_b32_e32 v18, 16, v213
	v_mul_f32_e32 v18, 0x3fd744fd, v18
	v_fmac_f32_e32 v18, v19, v209
	v_cvt_pk_bf16_f32 v16, v18, s0
	ds_write_b16 v61, v16 offset:5136
	v_or_b32_e32 v16, 48, v60
	v_cmp_lt_i32_e32 vcc, s9, v16
	v_cvt_pk_bf16_f32 v19, v21, s0
	ds_write_b16 v61, v19 offset:4704
	v_cndmask_b32_e32 v136, 0, v17, vcc
	v_ashrrev_i32_e32 v17, 31, v16
	v_lshl_add_u64 v[18:19], v[136:137], 0, s[0:1]
	v_lshlrev_b64 v[16:17], 12, v[16:17]
	v_mad_u64_u32 v[20:21], s[6:7], v18, s5, v[64:65]
	v_lshl_add_u64 v[22:23], v[62:63], 0, v[16:17]
	global_load_ushort v214, v[22:23], off
	v_mad_i32_i24 v21, v19, s5, v21
	v_lshl_add_u64 v[20:21], v[20:21], 0, v[66:67]
	global_load_dword v215, v[20:21], off
	v_or_b32_e32 v18, 49, v60
	v_ashrrev_i32_e32 v19, 31, v18
	v_lshlrev_b64 v[18:19], 12, v[18:19]
	s_ashr_i32 s5, s4, 31
	s_lshl_b64 s[4:5], s[4:5], 1
	s_add_u32 s4, s46, s4
	s_addc_u32 s5, s47, s5
	v_lshlrev_b32_e32 v136, 1, v73
	s_add_i32 s8, s8, 1
	s_mov_b64 s[6:7], 0
	s_waitcnt vmcnt(1)
	v_lshlrev_b32_e32 v16, 16, v214
	v_mul_f32_e32 v29, 0x3fd744fd, v16
	v_lshl_add_u64 v[16:17], v[62:63], 0, v[18:19]
	global_load_ushort v216, v[16:17], off
	s_waitcnt vmcnt(1)
	v_fmac_f32_e32 v29, v12, v215
	v_lshl_add_u64 v[18:19], v[62:63], 0, v[24:25]
	global_load_ushort v217, v[18:19], off
	s_waitcnt vmcnt(1)
	v_lshlrev_b32_e32 v12, 16, v216
	v_mul_f32_e32 v30, 0x3fd744fd, v12
	v_fmac_f32_e32 v30, v13, v215
	s_waitcnt vmcnt(0)
	v_lshlrev_b32_e32 v12, 16, v217
	v_mul_f32_e32 v24, 0x3fd744fd, v12
	v_lshl_add_u64 v[12:13], v[62:63], 0, v[26:27]
	global_load_ushort v218, v[12:13], off
	global_load_dword v219, v[20:21], off offset:64
	global_load_ushort v220, v[22:23], off offset:32
	global_load_ushort v221, v[16:17], off offset:32
	global_load_ushort v222, v[18:19], off offset:32
	global_load_ushort v223, v[12:13], off offset:32
	global_load_dword v224, v[20:21], off offset:128
	global_load_ushort v225, v[22:23], off offset:64
	global_load_ushort v226, v[16:17], off offset:64
	global_load_ushort v227, v[18:19], off offset:64
	global_load_ushort v228, v[12:13], off offset:64
	global_load_dword v229, v[20:21], off offset:192
	global_load_ushort v230, v[22:23], off offset:96
	global_load_ushort v231, v[16:17], off offset:96
	global_load_ushort v232, v[18:19], off offset:96
	global_load_ushort v233, v[12:13], off offset:96
	v_fmac_f32_e32 v24, v14, v215
	s_waitcnt vmcnt(15)
	v_lshlrev_b32_e32 v14, 16, v218
	v_mul_f32_e32 v14, 0x3fd744fd, v14
	v_fmac_f32_e32 v14, v15, v215
	v_cvt_pk_bf16_f32 v15, v29, s0
	ds_write_b16 v61, v15 offset:6912
	v_cvt_pk_bf16_f32 v15, v30, s0
	ds_write_b16 v61, v15 offset:7056
	v_cvt_pk_bf16_f32 v15, v24, s0
	v_cvt_pk_bf16_f32 v14, v14, s0
	ds_write_b16 v61, v15 offset:7200
	ds_write_b16 v61, v14 offset:7344
	s_waitcnt vmcnt(13)
	v_lshlrev_b32_e32 v15, 16, v220
	v_mul_f32_e32 v15, 0x3fd744fd, v15
	v_fmac_f32_e32 v15, v8, v219
	s_waitcnt vmcnt(12)
	v_lshlrev_b32_e32 v8, 16, v221
	v_mul_f32_e32 v8, 0x3fd744fd, v8
	v_fmac_f32_e32 v8, v9, v219
	v_cvt_pk_bf16_f32 v8, v8, s0
	ds_write_b16 v61, v8 offset:7088
	s_waitcnt vmcnt(11)
	v_lshlrev_b32_e32 v9, 16, v222
	v_mul_f32_e32 v9, 0x3fd744fd, v9
	v_fmac_f32_e32 v9, v10, v219
	v_cvt_pk_bf16_f32 v8, v9, s0
	ds_write_b16 v61, v8 offset:7232
	s_waitcnt vmcnt(10)
	v_lshlrev_b32_e32 v10, 16, v223
	v_mul_f32_e32 v10, 0x3fd744fd, v10
	v_fmac_f32_e32 v10, v11, v219
	v_cvt_pk_bf16_f32 v11, v15, s0
	v_cvt_pk_bf16_f32 v8, v10, s0
	ds_write_b16 v61, v11 offset:6944
	ds_write_b16 v61, v8 offset:7376
	s_waitcnt vmcnt(8)
	v_lshlrev_b32_e32 v9, 16, v225
	v_mul_f32_e32 v9, 0x3fd744fd, v9
	v_fmac_f32_e32 v9, v4, v224
	s_waitcnt vmcnt(7)
	v_lshlrev_b32_e32 v4, 16, v226
	v_mul_f32_e32 v4, 0x3fd744fd, v4
	v_fmac_f32_e32 v4, v5, v224
	v_cvt_pk_bf16_f32 v4, v4, s0
	ds_write_b16 v61, v4 offset:7120
	s_waitcnt vmcnt(6)
	v_lshlrev_b32_e32 v5, 16, v227
	v_mul_f32_e32 v5, 0x3fd744fd, v5
	v_fmac_f32_e32 v5, v6, v224
	v_cvt_pk_bf16_f32 v4, v5, s0
	ds_write_b16 v61, v4 offset:7264
	s_waitcnt vmcnt(5)
	v_lshlrev_b32_e32 v6, 16, v228
	v_mul_f32_e32 v6, 0x3fd744fd, v6
	v_fmac_f32_e32 v6, v7, v224
	v_cvt_pk_bf16_f32 v7, v9, s0
	v_cvt_pk_bf16_f32 v4, v6, s0
	ds_write_b16 v61, v7 offset:6976
	ds_write_b16 v61, v4 offset:7408
	s_waitcnt vmcnt(3)
	v_lshlrev_b32_e32 v5, 16, v230
	v_mul_f32_e32 v5, 0x3fd744fd, v5
	v_fmac_f32_e32 v5, v0, v229
	s_waitcnt vmcnt(2)
	v_lshlrev_b32_e32 v0, 16, v231
	v_mul_f32_e32 v0, 0x3fd744fd, v0
	v_fmac_f32_e32 v0, v1, v229
	v_cvt_pk_bf16_f32 v0, v0, s0
	ds_write_b16 v61, v0 offset:7152
	s_waitcnt vmcnt(1)
	v_lshlrev_b32_e32 v1, 16, v232
	v_mul_f32_e32 v1, 0x3fd744fd, v1
	v_fmac_f32_e32 v1, v2, v229
	v_cvt_pk_bf16_f32 v0, v1, s0
	ds_write_b16 v61, v0 offset:7296
	v_mov_b32_e32 v1, v137
	s_waitcnt vmcnt(0)
	v_lshlrev_b32_e32 v2, 16, v233
	v_mul_f32_e32 v2, 0x3fd744fd, v2
	v_fmac_f32_e32 v2, v3, v229
	v_cvt_pk_bf16_f32 v0, v2, s0
	ds_write_b16 v61, v0 offset:7440
	v_lshlrev_b32_e32 v0, 4, v71
	v_cvt_pk_bf16_f32 v3, v5, s0
	v_and_b32_e32 v0, 0x70, v0
	ds_write_b16 v61, v3 offset:7008
	v_or_b32_e32 v6, v74, v0
	v_lshl_add_u64 v[2:3], s[4:5], 0, v[136:137]
	s_movk_i32 s4, 0x90
	v_mad_u32_u24 v10, v70, s4, v6
	v_lshl_add_u64 v[4:5], v[2:3], 0, v[0:1]
	ds_read_b128 v[0:3], v10
	v_or_b32_e32 v6, v72, v70
	v_ashrrev_i32_e32 v7, 31, v6
	v_lshlrev_b64 v[8:9], 12, v[6:7]
	v_lshl_add_u64 v[8:9], v[4:5], 0, v[8:9]
	s_waitcnt lgkmcnt(0)
	global_store_dwordx4 v[8:9], v[0:3], off offset:2048
	ds_read_b128 v[0:3], v10 offset:1152
	v_or_b32_e32 v8, 8, v6
	v_ashrrev_i32_e32 v9, 31, v8
	v_lshlrev_b64 v[8:9], 12, v[8:9]
	v_lshl_add_u64 v[8:9], v[4:5], 0, v[8:9]
	s_waitcnt lgkmcnt(0)
	global_store_dwordx4 v[8:9], v[0:3], off offset:2048
	ds_read_b128 v[0:3], v10 offset:2304
	v_or_b32_e32 v8, 16, v6
	v_ashrrev_i32_e32 v9, 31, v8
	v_lshlrev_b64 v[8:9], 12, v[8:9]
	v_lshl_add_u64 v[8:9], v[4:5], 0, v[8:9]
	s_waitcnt lgkmcnt(0)
	global_store_dwordx4 v[8:9], v[0:3], off offset:2048
	ds_read_b128 v[0:3], v10 offset:3456
	v_or_b32_e32 v8, 24, v6
	v_ashrrev_i32_e32 v9, 31, v8
	v_lshlrev_b64 v[8:9], 12, v[8:9]
	v_lshl_add_u64 v[8:9], v[4:5], 0, v[8:9]
	s_waitcnt lgkmcnt(0)
	global_store_dwordx4 v[8:9], v[0:3], off offset:2048
	ds_read_b128 v[0:3], v10 offset:4608
	v_or_b32_e32 v8, 32, v6
	v_ashrrev_i32_e32 v9, 31, v8
	v_lshlrev_b64 v[8:9], 12, v[8:9]
	v_lshl_add_u64 v[8:9], v[4:5], 0, v[8:9]
	s_waitcnt lgkmcnt(0)
	global_store_dwordx4 v[8:9], v[0:3], off offset:2048
	ds_read_b128 v[0:3], v10 offset:5760
	v_or_b32_e32 v8, 40, v6
	v_ashrrev_i32_e32 v9, 31, v8
	v_lshlrev_b64 v[8:9], 12, v[8:9]
	v_lshl_add_u64 v[8:9], v[4:5], 0, v[8:9]
	s_waitcnt lgkmcnt(0)
	global_store_dwordx4 v[8:9], v[0:3], off offset:2048
	ds_read_b128 v[0:3], v10 offset:6912
	v_or_b32_e32 v8, 48, v6
	v_ashrrev_i32_e32 v9, 31, v8
	v_lshlrev_b64 v[8:9], 12, v[8:9]
	v_lshl_add_u64 v[8:9], v[4:5], 0, v[8:9]
	s_waitcnt lgkmcnt(0)
	global_store_dwordx4 v[8:9], v[0:3], off offset:2048
	ds_read_b128 v[0:3], v10 offset:8064
	v_or_b32_e32 v6, 56, v6
	v_ashrrev_i32_e32 v7, 31, v6
	v_lshlrev_b64 v[6:7], 12, v[6:7]
	v_lshl_add_u64 v[4:5], v[4:5], 0, v[6:7]
	s_waitcnt lgkmcnt(0)
	global_store_dwordx4 v[4:5], v[0:3], off offset:2048
	s_barrier
	s_branch .LBB0_52

.LBB0_172:
	s_and_b32 s10, s9, 0x8000
	s_xor_b32 s11, s10, 0x8000
	v_add_u32_e32 v79, s11, v72
	v_lshl_add_u64 v[80:81], v[64:65], 0, s[6:7]
	v_readfirstlane_b32 s11, v79
	v_lshl_add_u64 v[82:83], v[80:81], 0, s[28:29]
	s_mov_b32 m0, s11
	v_lshl_add_u64 v[84:85], v[66:67], 0, s[6:7]
	global_load_lds_dwordx4 v[82:83], off
	v_add_u32_e32 v82, 0x4000, v79
	v_lshl_add_u64 v[86:87], v[84:85], 0, s[28:29]
	v_readfirstlane_b32 s11, v82
	s_mov_b32 m0, s11
	v_lshl_add_u64 v[82:83], v[80:81], 0, s[12:13]
	global_load_lds_dwordx4 v[86:87], off
	v_add_u32_e32 v86, 0x1000, v79
	s_nop 0
	v_readfirstlane_b32 s11, v86
	v_add_u32_e32 v86, 0x5000, v79
	s_mov_b32 m0, s11
	v_readfirstlane_b32 s11, v86
	v_add_u32_e32 v86, 0x2000, v79
	global_load_lds_dwordx4 v[82:83], off
	v_lshl_add_u64 v[82:83], v[84:85], 0, s[12:13]
	s_mov_b32 m0, s11
	v_readfirstlane_b32 s11, v86
	v_add_u32_e32 v86, 0x6000, v79
	global_load_lds_dwordx4 v[82:83], off
	v_lshl_add_u64 v[82:83], v[80:81], 0, s[16:17]
	s_mov_b32 m0, s11
	v_readfirstlane_b32 s11, v86
	global_load_lds_dwordx4 v[82:83], off
	v_lshl_add_u64 v[82:83], v[84:85], 0, s[16:17]
	s_mov_b32 m0, s11
	v_lshl_add_u64 v[80:81], v[80:81], 0, s[14:15]
	global_load_lds_dwordx4 v[82:83], off
	v_add_u32_e32 v82, 0x3000, v79
	v_add_u32_e32 v79, 0x7000, v79
	v_readfirstlane_b32 s11, v82
	s_mov_b32 m0, s11
	v_readfirstlane_b32 s11, v79
	global_load_lds_dwordx4 v[80:81], off
	v_lshl_add_u64 v[80:81], v[84:85], 0, s[14:15]
	s_mov_b32 m0, s11
	v_or_b32_e32 v79, s10, v78
	global_load_lds_dwordx4 v[80:81], off
	v_add_u32_e32 v100, v79, v73
	v_add_u32_e32 v79, v79, v74
	ds_read_b128 v[80:83], v100
	ds_read_b128 v[84:87], v100 offset:2048
	ds_read_b128 v[88:91], v79 offset:16384
	ds_read_b128 v[92:95], v79 offset:18432
	ds_read_b128 v[96:99], v100 offset:4096
	ds_read_b128 v[100:103], v100 offset:6144
	ds_read_b128 v[104:107], v79 offset:20480
	ds_read_b128 v[108:111], v79 offset:22528
	v_or_b32_e32 v79, s10, v77
	v_add_u32_e32 v132, v79, v73
	v_add_u32_e32 v79, v79, v74
	ds_read_b128 v[112:115], v132
	ds_read_b128 v[116:119], v132 offset:2048
	ds_read_b128 v[120:123], v79 offset:16384
	ds_read_b128 v[124:127], v79 offset:18432
	ds_read_b128 v[128:131], v132 offset:4096
	ds_read_b128 v[132:135], v132 offset:6144
	ds_read_b128 v[146:149], v79 offset:20480
	ds_read_b128 v[150:153], v79 offset:22528
	s_waitcnt lgkmcnt(0)
	v_mfma_f32_16x16x32_bf16 v[60:63], v[80:83], v[88:91], v[60:63]
	v_mfma_f32_16x16x32_bf16 v[56:59], v[80:83], v[92:95], v[56:59]
	v_mfma_f32_16x16x32_bf16 v[52:55], v[80:83], v[104:107], v[52:55]
	v_mfma_f32_16x16x32_bf16 v[48:51], v[80:83], v[108:111], v[48:51]
	v_mfma_f32_16x16x32_bf16 v[44:47], v[84:87], v[88:91], v[44:47]
	v_mfma_f32_16x16x32_bf16 v[40:43], v[84:87], v[92:95], v[40:43]
	v_mfma_f32_16x16x32_bf16 v[36:39], v[84:87], v[104:107], v[36:39]
	v_mfma_f32_16x16x32_bf16 v[32:35], v[84:87], v[108:111], v[32:35]
	v_mfma_f32_16x16x32_bf16 v[28:31], v[96:99], v[88:91], v[28:31]
	v_mfma_f32_16x16x32_bf16 v[24:27], v[96:99], v[92:95], v[24:27]
	v_mfma_f32_16x16x32_bf16 v[20:23], v[96:99], v[104:107], v[20:23]
	v_mfma_f32_16x16x32_bf16 v[16:19], v[96:99], v[108:111], v[16:19]
	v_mfma_f32_16x16x32_bf16 v[12:15], v[100:103], v[88:91], v[12:15]
	v_mfma_f32_16x16x32_bf16 v[8:11], v[100:103], v[92:95], v[8:11]
	v_mfma_f32_16x16x32_bf16 v[4:7], v[100:103], v[104:107], v[4:7]
	v_mfma_f32_16x16x32_bf16 v[0:3], v[100:103], v[108:111], v[0:3]
	v_mfma_f32_16x16x32_bf16 v[60:63], v[112:115], v[120:123], v[60:63]
	v_mfma_f32_16x16x32_bf16 v[56:59], v[112:115], v[124:127], v[56:59]
	v_mfma_f32_16x16x32_bf16 v[52:55], v[112:115], v[146:149], v[52:55]
	v_mfma_f32_16x16x32_bf16 v[48:51], v[112:115], v[150:153], v[48:51]
	v_mfma_f32_16x16x32_bf16 v[44:47], v[116:119], v[120:123], v[44:47]
	v_mfma_f32_16x16x32_bf16 v[40:43], v[116:119], v[124:127], v[40:43]
	v_mfma_f32_16x16x32_bf16 v[36:39], v[116:119], v[146:149], v[36:39]
	v_mfma_f32_16x16x32_bf16 v[32:35], v[116:119], v[150:153], v[32:35]
	v_mfma_f32_16x16x32_bf16 v[28:31], v[128:131], v[120:123], v[28:31]
	v_mfma_f32_16x16x32_bf16 v[24:27], v[128:131], v[124:127], v[24:27]
	v_mfma_f32_16x16x32_bf16 v[20:23], v[128:131], v[146:149], v[20:23]
	v_mfma_f32_16x16x32_bf16 v[16:19], v[128:131], v[150:153], v[16:19]
	v_mfma_f32_16x16x32_bf16 v[12:15], v[132:135], v[120:123], v[12:15]
	v_mfma_f32_16x16x32_bf16 v[8:11], v[132:135], v[124:127], v[8:11]
	v_mfma_f32_16x16x32_bf16 v[4:7], v[132:135], v[146:149], v[4:7]
	v_mfma_f32_16x16x32_bf16 v[0:3], v[132:135], v[150:153], v[0:3]
	s_waitcnt vmcnt(0)
	s_add_u32 s6, s6, 0x80
	s_addc_u32 s7, s7, 0
	s_add_i32 s9, s9, 0x8000
	s_cmpk_eq_i32 s6, 0x780
	s_barrier
	s_cbranch_scc0 .LBB0_172
	v_add_u32_e32 v72, v78, v73
	v_add_u32_e32 v102, v78, v74
	ds_read_b128 v[64:67], v72 offset:32768
	ds_read_b128 v[78:81], v72 offset:34816
	ds_read_b128 v[82:85], v102 offset:49152
	ds_read_b128 v[86:89], v102 offset:51200
	ds_read_b128 v[90:93], v72 offset:36864
	ds_read_b128 v[94:97], v72 offset:38912
	ds_read_b128 v[98:101], v102 offset:53248
	ds_read_b128 v[102:105], v102 offset:55296
	v_add_u32_e32 v72, v77, v73
	v_add_u32_e32 v73, v77, v74
	ds_read_b128 v[106:109], v72 offset:32768
	ds_read_b128 v[110:113], v72 offset:34816
	ds_read_b128 v[114:117], v73 offset:49152
	ds_read_b128 v[118:121], v73 offset:51200
	ds_read_b128 v[122:125], v72 offset:36864
	ds_read_b128 v[126:129], v72 offset:38912
	ds_read_b128 v[130:133], v73 offset:53248
	ds_read_b128 v[146:149], v73 offset:55296
	s_waitcnt lgkmcnt(13)
	v_mfma_f32_16x16x32_bf16 v[60:63], v[64:67], v[82:85], v[60:63]
	s_waitcnt lgkmcnt(12)
	v_mfma_f32_16x16x32_bf16 v[56:59], v[64:67], v[86:89], v[56:59]
	s_waitcnt lgkmcnt(9)
	v_mfma_f32_16x16x32_bf16 v[52:55], v[64:67], v[98:101], v[52:55]
	s_waitcnt lgkmcnt(8)
	v_mfma_f32_16x16x32_bf16 v[48:51], v[64:67], v[102:105], v[48:51]
	v_mfma_f32_16x16x32_bf16 v[44:47], v[78:81], v[82:85], v[44:47]
	v_mfma_f32_16x16x32_bf16 v[40:43], v[78:81], v[86:89], v[40:43]
	v_mfma_f32_16x16x32_bf16 v[36:39], v[78:81], v[98:101], v[36:39]
	v_mfma_f32_16x16x32_bf16 v[32:35], v[78:81], v[102:105], v[32:35]
	v_mfma_f32_16x16x32_bf16 v[28:31], v[90:93], v[82:85], v[28:31]
	v_mfma_f32_16x16x32_bf16 v[24:27], v[90:93], v[86:89], v[24:27]
	v_mfma_f32_16x16x32_bf16 v[20:23], v[90:93], v[98:101], v[20:23]
	v_mfma_f32_16x16x32_bf16 v[16:19], v[90:93], v[102:105], v[16:19]
	v_mfma_f32_16x16x32_bf16 v[12:15], v[94:97], v[82:85], v[12:15]
	v_mfma_f32_16x16x32_bf16 v[8:11], v[94:97], v[86:89], v[8:11]
	v_mfma_f32_16x16x32_bf16 v[4:7], v[94:97], v[98:101], v[4:7]
	v_mfma_f32_16x16x32_bf16 v[0:3], v[94:97], v[102:105], v[0:3]
	s_waitcnt lgkmcnt(5)
	v_mfma_f32_16x16x32_bf16 v[78:81], v[106:109], v[114:117], v[60:63]
	s_waitcnt lgkmcnt(4)
	v_mfma_f32_16x16x32_bf16 v[56:59], v[106:109], v[118:121], v[56:59]
	s_waitcnt lgkmcnt(1)
	v_mfma_f32_16x16x32_bf16 v[52:55], v[106:109], v[130:133], v[52:55]
	s_waitcnt lgkmcnt(0)
	v_mfma_f32_16x16x32_bf16 v[48:51], v[106:109], v[146:149], v[48:51]
	v_mfma_f32_16x16x32_bf16 v[44:47], v[110:113], v[114:117], v[44:47]
	v_mfma_f32_16x16x32_bf16 v[40:43], v[110:113], v[118:121], v[40:43]
	v_mfma_f32_16x16x32_bf16 v[36:39], v[110:113], v[130:133], v[36:39]
	v_mfma_f32_16x16x32_bf16 v[32:35], v[110:113], v[146:149], v[32:35]
	v_mfma_f32_16x16x32_bf16 v[28:31], v[122:125], v[114:117], v[28:31]
	v_mfma_f32_16x16x32_bf16 v[24:27], v[122:125], v[118:121], v[24:27]
	v_mfma_f32_16x16x32_bf16 v[20:23], v[122:125], v[130:133], v[20:23]
	v_mfma_f32_16x16x32_bf16 v[16:19], v[122:125], v[146:149], v[16:19]
	v_mfma_f32_16x16x32_bf16 v[12:15], v[126:129], v[114:117], v[12:15]
	v_mfma_f32_16x16x32_bf16 v[8:11], v[126:129], v[118:121], v[8:11]
	v_mfma_f32_16x16x32_bf16 v[4:7], v[126:129], v[130:133], v[4:7]
	v_mfma_f32_16x16x32_bf16 v[0:3], v[126:129], v[146:149], v[0:3]
	v_add_u32_e32 v72, s5, v69
	v_add_u32_e32 v61, 0xfffff000, v72
	s_movk_i32 s6, 0x2400
	v_lshl_or_b32 v60, v75, 2, v72
	v_lshrrev_b32_e32 v61, 12, v61
	s_movk_i32 s9, 0xfff
	v_mul_lo_u32 v74, v68, s6
	v_add_u32_e32 v61, 1, v61
	v_cmp_lt_i32_e32 vcc, s9, v60
	v_readlane_b32 s6, v245, 44
	v_readlane_b32 s7, v245, 45
	v_cndmask_b32_e32 v136, 0, v61, vcc
	v_lshl_add_u64 v[66:67], v[136:137], 0, s[0:1]
	v_mov_b64_e32 v[64:65], s[6:7]
	s_movk_i32 s5, 0x6000
	v_mad_u64_u32 v[68:69], s[6:7], v66, s5, v[64:65]
	v_or_b32_e32 v66, 1, v60
	v_mad_i32_i24 v69, v67, s5, v69
	v_ashrrev_i32_e32 v67, 31, v66
	v_lshlrev_b64 v[84:85], 12, v[66:67]
	v_or_b32_e32 v66, 2, v60
	v_and_b32_e32 v73, 64, v71
	v_ashrrev_i32_e32 v67, 31, v66
	v_or3_b32 v62, v76, s4, v73
	v_lshlrev_b64 v[86:87], 12, v[66:67]
	v_or_b32_e32 v66, 3, v60
	v_readlane_b32 s36, v247, 57
	v_ashrrev_i32_e32 v61, 31, v60
	v_ashrrev_i32_e32 v67, 31, v66
	v_ashrrev_i32_e32 v63, 31, v62
	v_readlane_b32 s46, v246, 3
	v_readlane_b32 s47, v246, 4
	v_lshlrev_b64 v[82:83], 12, v[60:61]
	v_lshlrev_b64 v[88:89], 12, v[66:67]
	v_lshlrev_b64 v[66:67], 2, v[62:63]
	v_lshl_add_u64 v[62:63], v[62:63], 1, s[46:47]
	v_lshl_add_u64 v[82:83], v[62:63], 0, v[82:83]
	s_waitcnt vmcnt(0)
	s_barrier
	global_load_ushort v202, v[82:83], off
	v_lshl_add_u64 v[68:69], v[68:69], 0, v[66:67]
	global_load_dword v203, v[68:69], off
	v_lshl_add_u64 v[84:85], v[62:63], 0, v[84:85]
	global_load_ushort v204, v[84:85], off
	s_movk_i32 s6, 0x240
	s_movk_i32 s36, 0x880
	v_readlane_b32 s37, v247, 58
	v_readlane_b32 s38, v247, 59
	v_readlane_b32 s39, v247, 60
	v_readlane_b32 s40, v247, 61
	v_readlane_b32 s41, v247, 62
	v_readlane_b32 s42, v247, 63
	v_readlane_b32 s43, v246, 0
	v_readlane_b32 s44, v246, 1
	v_readlane_b32 s45, v246, 2
	v_readlane_b32 s48, v246, 5
	v_readlane_b32 s49, v246, 6
	v_readlane_b32 s50, v246, 7
	v_readlane_b32 s51, v246, 8
	s_waitcnt vmcnt(2)
	v_lshlrev_b32_e32 v77, 16, v202
	v_mul_f32_e32 v77, 0x3fd744fd, v77
	s_waitcnt vmcnt(1)
	v_fmac_f32_e32 v77, v78, v203
	s_waitcnt vmcnt(0)
	v_lshlrev_b32_e32 v78, 16, v204
	v_mul_f32_e32 v90, 0x3fd744fd, v78
	v_fmac_f32_e32 v90, v79, v203
	v_lshl_add_u64 v[78:79], v[62:63], 0, v[86:87]
	global_load_ushort v205, v[78:79], off
	s_waitcnt vmcnt(0)
	v_lshlrev_b32_e32 v86, 16, v205
	v_mul_f32_e32 v91, 0x3fd744fd, v86
	v_lshl_add_u64 v[86:87], v[62:63], 0, v[88:89]
	global_load_ushort v206, v[86:87], off
	global_load_dword v207, v[68:69], off offset:64
	global_load_ushort v208, v[82:83], off offset:32
	global_load_ushort v209, v[84:85], off offset:32
	global_load_ushort v210, v[78:79], off offset:32
	global_load_ushort v211, v[86:87], off offset:32
	global_load_dword v212, v[68:69], off offset:128
	global_load_ushort v213, v[82:83], off offset:64
	global_load_ushort v214, v[84:85], off offset:64
	global_load_ushort v215, v[78:79], off offset:64
	global_load_ushort v216, v[86:87], off offset:64
	global_load_dword v217, v[68:69], off offset:192
	global_load_ushort v218, v[82:83], off offset:96
	global_load_ushort v219, v[84:85], off offset:96
	global_load_ushort v220, v[78:79], off offset:96
	global_load_ushort v221, v[86:87], off offset:96
	v_fmac_f32_e32 v91, v80, v203
	s_waitcnt vmcnt(15)
	v_lshlrev_b32_e32 v80, 16, v206
	v_mul_f32_e32 v80, 0x3fd744fd, v80
	v_fmac_f32_e32 v80, v81, v203
	v_lshl_or_b32 v61, v76, 1, v74
	v_mad_u32_u24 v61, v75, s6, v61
	v_cvt_pk_bf16_f32 v75, v90, s0
	ds_write_b16 v61, v75 offset:144
	v_cvt_pk_bf16_f32 v75, v91, s0
	v_cvt_pk_bf16_f32 v76, v77, s0
	ds_write_b16 v61, v75 offset:288
	v_cvt_pk_bf16_f32 v75, v80, s0
	ds_write_b16 v61, v76
	ds_write_b16 v61, v75 offset:432
	s_waitcnt vmcnt(13)
	v_lshlrev_b32_e32 v76, 16, v208
	v_mul_f32_e32 v76, 0x3fd744fd, v76
	v_fmac_f32_e32 v76, v56, v207
	s_waitcnt vmcnt(12)
	v_lshlrev_b32_e32 v56, 16, v209
	v_mul_f32_e32 v56, 0x3fd744fd, v56
	v_fmac_f32_e32 v56, v57, v207
	v_cvt_pk_bf16_f32 v56, v56, s0
	ds_write_b16 v61, v56 offset:176
	s_waitcnt vmcnt(11)
	v_lshlrev_b32_e32 v57, 16, v210
	v_mul_f32_e32 v57, 0x3fd744fd, v57
	v_fmac_f32_e32 v57, v58, v207
	v_cvt_pk_bf16_f32 v56, v57, s0
	ds_write_b16 v61, v56 offset:320
	s_waitcnt vmcnt(10)
	v_lshlrev_b32_e32 v58, 16, v211
	v_mul_f32_e32 v58, 0x3fd744fd, v58
	v_fmac_f32_e32 v58, v59, v207
	v_cvt_pk_bf16_f32 v59, v76, s0
	v_cvt_pk_bf16_f32 v56, v58, s0
	ds_write_b16 v61, v59 offset:32
	ds_write_b16 v61, v56 offset:464
	s_waitcnt vmcnt(8)
	v_lshlrev_b32_e32 v57, 16, v213
	v_mul_f32_e32 v57, 0x3fd744fd, v57
	v_fmac_f32_e32 v57, v52, v212
	s_waitcnt vmcnt(7)
	v_lshlrev_b32_e32 v52, 16, v214
	v_mul_f32_e32 v52, 0x3fd744fd, v52
	v_fmac_f32_e32 v52, v53, v212
	v_cvt_pk_bf16_f32 v52, v52, s0
	ds_write_b16 v61, v52 offset:208
	s_waitcnt vmcnt(6)
	v_lshlrev_b32_e32 v53, 16, v215
	v_mul_f32_e32 v53, 0x3fd744fd, v53
	v_fmac_f32_e32 v53, v54, v212
	v_cvt_pk_bf16_f32 v52, v53, s0
	ds_write_b16 v61, v52 offset:352
	s_waitcnt vmcnt(5)
	v_lshlrev_b32_e32 v54, 16, v216
	v_mul_f32_e32 v54, 0x3fd744fd, v54
	v_fmac_f32_e32 v54, v55, v212
	v_cvt_pk_bf16_f32 v55, v57, s0
	v_cvt_pk_bf16_f32 v52, v54, s0
	ds_write_b16 v61, v55 offset:64
	ds_write_b16 v61, v52 offset:496
	v_or_b32_e32 v54, 18, v60
	v_ashrrev_i32_e32 v55, 31, v54
	v_lshlrev_b64 v[56:57], 12, v[54:55]
	v_or_b32_e32 v54, 19, v60
	v_ashrrev_i32_e32 v55, 31, v54
	v_lshlrev_b64 v[58:59], 12, v[54:55]
	s_waitcnt vmcnt(3)
	v_lshlrev_b32_e32 v53, 16, v218
	v_mul_f32_e32 v53, 0x3fd744fd, v53
	v_fmac_f32_e32 v53, v48, v217
	s_waitcnt vmcnt(2)
	v_lshlrev_b32_e32 v48, 16, v219
	v_mul_f32_e32 v48, 0x3fd744fd, v48
	v_fmac_f32_e32 v48, v49, v217
	v_cvt_pk_bf16_f32 v48, v48, s0
	ds_write_b16 v61, v48 offset:240
	s_waitcnt vmcnt(1)
	v_lshlrev_b32_e32 v49, 16, v220
	v_mul_f32_e32 v49, 0x3fd744fd, v49
	v_fmac_f32_e32 v49, v50, v217
	v_cvt_pk_bf16_f32 v48, v49, s0
	ds_write_b16 v61, v48 offset:384
	v_add_u32_e32 v49, 0xfffff010, v72
	v_lshrrev_b32_e32 v49, 12, v49
	v_add_u32_e32 v49, 1, v49
	s_waitcnt vmcnt(0)
	v_lshlrev_b32_e32 v50, 16, v221
	v_mul_f32_e32 v50, 0x3fd744fd, v50
	v_fmac_f32_e32 v50, v51, v217
	v_cvt_pk_bf16_f32 v48, v50, s0
	ds_write_b16 v61, v48 offset:528
	v_or_b32_e32 v48, 16, v60
	v_cmp_lt_i32_e32 vcc, s9, v48
	v_cvt_pk_bf16_f32 v51, v53, s0
	ds_write_b16 v61, v51 offset:96
	v_cndmask_b32_e32 v136, 0, v49, vcc
	v_ashrrev_i32_e32 v49, 31, v48
	v_lshl_add_u64 v[50:51], v[136:137], 0, s[0:1]
	v_lshlrev_b64 v[48:49], 12, v[48:49]
	v_mad_u64_u32 v[52:53], s[6:7], v50, s5, v[64:65]
	v_lshl_add_u64 v[54:55], v[62:63], 0, v[48:49]
	global_load_ushort v222, v[54:55], off
	v_mad_i32_i24 v53, v51, s5, v53
	v_lshl_add_u64 v[52:53], v[52:53], 0, v[66:67]
	global_load_dword v223, v[52:53], off
	v_or_b32_e32 v50, 17, v60
	v_ashrrev_i32_e32 v51, 31, v50
	v_lshlrev_b64 v[50:51], 12, v[50:51]
	s_waitcnt vmcnt(1)
	v_lshlrev_b32_e32 v48, 16, v222
	v_mul_f32_e32 v69, 0x3fd744fd, v48
	v_lshl_add_u64 v[48:49], v[62:63], 0, v[50:51]
	global_load_ushort v224, v[48:49], off
	s_waitcnt vmcnt(1)
	v_fmac_f32_e32 v69, v44, v223
	v_lshl_add_u64 v[50:51], v[62:63], 0, v[56:57]
	global_load_ushort v225, v[50:51], off
	s_waitcnt vmcnt(1)
	v_lshlrev_b32_e32 v44, 16, v224
	v_mul_f32_e32 v75, 0x3fd744fd, v44
	v_fmac_f32_e32 v75, v45, v223
	s_waitcnt vmcnt(0)
	v_lshlrev_b32_e32 v44, 16, v225
	v_mul_f32_e32 v56, 0x3fd744fd, v44
	v_lshl_add_u64 v[44:45], v[62:63], 0, v[58:59]
	global_load_ushort v226, v[44:45], off
	global_load_dword v227, v[52:53], off offset:64
	global_load_ushort v228, v[54:55], off offset:32
	global_load_ushort v229, v[48:49], off offset:32
	global_load_ushort v230, v[50:51], off offset:32
	global_load_ushort v231, v[44:45], off offset:32
	global_load_dword v232, v[52:53], off offset:128
	global_load_ushort v233, v[54:55], off offset:64
	global_load_ushort v234, v[48:49], off offset:64
	global_load_ushort v235, v[50:51], off offset:64
	global_load_ushort v236, v[44:45], off offset:64
	global_load_dword v237, v[52:53], off offset:192
	global_load_ushort v238, v[54:55], off offset:96
	global_load_ushort v239, v[48:49], off offset:96
	global_load_ushort v240, v[50:51], off offset:96
	global_load_ushort v241, v[44:45], off offset:96
	v_fmac_f32_e32 v56, v46, v223
	s_waitcnt vmcnt(15)
	v_lshlrev_b32_e32 v46, 16, v226
	v_mul_f32_e32 v46, 0x3fd744fd, v46
	v_fmac_f32_e32 v46, v47, v223
	v_cvt_pk_bf16_f32 v47, v69, s0
	ds_write_b16 v61, v47 offset:2304
	v_cvt_pk_bf16_f32 v47, v75, s0
	ds_write_b16 v61, v47 offset:2448
	v_cvt_pk_bf16_f32 v47, v56, s0
	v_cvt_pk_bf16_f32 v46, v46, s0
	ds_write_b16 v61, v47 offset:2592
	ds_write_b16 v61, v46 offset:2736
	s_waitcnt vmcnt(13)
	v_lshlrev_b32_e32 v47, 16, v228
	v_mul_f32_e32 v47, 0x3fd744fd, v47
	v_fmac_f32_e32 v47, v40, v227
	s_waitcnt vmcnt(12)
	v_lshlrev_b32_e32 v40, 16, v229
	v_mul_f32_e32 v40, 0x3fd744fd, v40
	v_fmac_f32_e32 v40, v41, v227
	v_cvt_pk_bf16_f32 v40, v40, s0
	ds_write_b16 v61, v40 offset:2480
	s_waitcnt vmcnt(11)
	v_lshlrev_b32_e32 v41, 16, v230
	v_mul_f32_e32 v41, 0x3fd744fd, v41
	v_fmac_f32_e32 v41, v42, v227
	v_cvt_pk_bf16_f32 v40, v41, s0
	ds_write_b16 v61, v40 offset:2624
	s_waitcnt vmcnt(10)
	v_lshlrev_b32_e32 v42, 16, v231
	v_mul_f32_e32 v42, 0x3fd744fd, v42
	v_fmac_f32_e32 v42, v43, v227
	v_cvt_pk_bf16_f32 v43, v47, s0
	v_cvt_pk_bf16_f32 v40, v42, s0
	ds_write_b16 v61, v43 offset:2336
	ds_write_b16 v61, v40 offset:2768
	s_waitcnt vmcnt(8)
	v_lshlrev_b32_e32 v41, 16, v233
	v_mul_f32_e32 v41, 0x3fd744fd, v41
	v_fmac_f32_e32 v41, v36, v232
	s_waitcnt vmcnt(7)
	v_lshlrev_b32_e32 v36, 16, v234
	v_mul_f32_e32 v36, 0x3fd744fd, v36
	v_fmac_f32_e32 v36, v37, v232
	v_cvt_pk_bf16_f32 v36, v36, s0
	ds_write_b16 v61, v36 offset:2512
	s_waitcnt vmcnt(6)
	v_lshlrev_b32_e32 v37, 16, v235
	v_mul_f32_e32 v37, 0x3fd744fd, v37
	v_fmac_f32_e32 v37, v38, v232
	v_cvt_pk_bf16_f32 v36, v37, s0
	ds_write_b16 v61, v36 offset:2656
	s_waitcnt vmcnt(5)
	v_lshlrev_b32_e32 v38, 16, v236
	v_mul_f32_e32 v38, 0x3fd744fd, v38
	v_fmac_f32_e32 v38, v39, v232
	v_cvt_pk_bf16_f32 v39, v41, s0
	v_cvt_pk_bf16_f32 v36, v38, s0
	ds_write_b16 v61, v39 offset:2368
	ds_write_b16 v61, v36 offset:2800
	v_or_b32_e32 v38, 34, v60
	v_ashrrev_i32_e32 v39, 31, v38
	v_lshlrev_b64 v[40:41], 12, v[38:39]
	v_or_b32_e32 v38, 35, v60
	v_ashrrev_i32_e32 v39, 31, v38
	v_lshlrev_b64 v[42:43], 12, v[38:39]
	s_waitcnt vmcnt(3)
	v_lshlrev_b32_e32 v37, 16, v238
	v_mul_f32_e32 v37, 0x3fd744fd, v37
	v_fmac_f32_e32 v37, v32, v237
	s_waitcnt vmcnt(2)
	v_lshlrev_b32_e32 v32, 16, v239
	v_mul_f32_e32 v32, 0x3fd744fd, v32
	v_fmac_f32_e32 v32, v33, v237
	v_cvt_pk_bf16_f32 v32, v32, s0
	ds_write_b16 v61, v32 offset:2544
	s_waitcnt vmcnt(1)
	v_lshlrev_b32_e32 v33, 16, v240
	v_mul_f32_e32 v33, 0x3fd744fd, v33
	v_fmac_f32_e32 v33, v34, v237
	v_cvt_pk_bf16_f32 v32, v33, s0
	ds_write_b16 v61, v32 offset:2688
	v_add_u32_e32 v33, 0xfffff020, v72
	v_lshrrev_b32_e32 v33, 12, v33
	v_add_u32_e32 v33, 1, v33
	s_waitcnt vmcnt(0)
	v_lshlrev_b32_e32 v34, 16, v241
	v_mul_f32_e32 v34, 0x3fd744fd, v34
	v_fmac_f32_e32 v34, v35, v237
	v_cvt_pk_bf16_f32 v32, v34, s0
	ds_write_b16 v61, v32 offset:2832
	v_or_b32_e32 v32, 32, v60
	v_cmp_lt_i32_e32 vcc, s9, v32
	v_cvt_pk_bf16_f32 v35, v37, s0
	ds_write_b16 v61, v35 offset:2400
	v_cndmask_b32_e32 v136, 0, v33, vcc
	v_ashrrev_i32_e32 v33, 31, v32
	v_lshl_add_u64 v[34:35], v[136:137], 0, s[0:1]
	v_lshlrev_b64 v[32:33], 12, v[32:33]
	v_mad_u64_u32 v[36:37], s[6:7], v34, s5, v[64:65]
	v_lshl_add_u64 v[38:39], v[62:63], 0, v[32:33]
	global_load_ushort v248, v[38:39], off
	v_mad_i32_i24 v37, v35, s5, v37
	v_lshl_add_u64 v[36:37], v[36:37], 0, v[66:67]
	global_load_dword v249, v[36:37], off
	v_or_b32_e32 v34, 33, v60
	v_ashrrev_i32_e32 v35, 31, v34
	v_lshlrev_b64 v[34:35], 12, v[34:35]
	s_waitcnt vmcnt(1)
	v_lshlrev_b32_e32 v32, 16, v248
	v_mul_f32_e32 v45, 0x3fd744fd, v32
	v_lshl_add_u64 v[32:33], v[62:63], 0, v[34:35]
	global_load_ushort v250, v[32:33], off
	s_waitcnt vmcnt(1)
	v_fmac_f32_e32 v45, v28, v249
	v_lshl_add_u64 v[34:35], v[62:63], 0, v[40:41]
	global_load_ushort v251, v[34:35], off
	s_waitcnt vmcnt(1)
	v_lshlrev_b32_e32 v28, 16, v250
	v_mul_f32_e32 v46, 0x3fd744fd, v28
	v_fmac_f32_e32 v46, v29, v249
	s_waitcnt vmcnt(0)
	v_lshlrev_b32_e32 v28, 16, v251
	v_mul_f32_e32 v40, 0x3fd744fd, v28
	v_lshl_add_u64 v[28:29], v[62:63], 0, v[42:43]
	global_load_ushort v252, v[28:29], off
	global_load_dword v253, v[36:37], off offset:64
	global_load_ushort v254, v[38:39], off offset:32
	global_load_ushort v255, v[32:33], off offset:32
	global_load_ushort v202, v[34:35], off offset:32
	global_load_ushort v203, v[28:29], off offset:32
	global_load_dword v204, v[36:37], off offset:128
	global_load_ushort v205, v[38:39], off offset:64
	global_load_ushort v206, v[32:33], off offset:64
	global_load_ushort v207, v[34:35], off offset:64
	global_load_ushort v208, v[28:29], off offset:64
	global_load_dword v209, v[36:37], off offset:192
	global_load_ushort v210, v[38:39], off offset:96
	global_load_ushort v211, v[32:33], off offset:96
	global_load_ushort v212, v[34:35], off offset:96
	global_load_ushort v213, v[28:29], off offset:96
	v_fmac_f32_e32 v40, v30, v249
	s_waitcnt vmcnt(15)
	v_lshlrev_b32_e32 v30, 16, v252
	v_mul_f32_e32 v30, 0x3fd744fd, v30
	v_fmac_f32_e32 v30, v31, v249
	v_cvt_pk_bf16_f32 v31, v45, s0
	ds_write_b16 v61, v31 offset:4608
	v_cvt_pk_bf16_f32 v31, v46, s0
	ds_write_b16 v61, v31 offset:4752
	v_cvt_pk_bf16_f32 v31, v40, s0
	v_cvt_pk_bf16_f32 v30, v30, s0
	ds_write_b16 v61, v31 offset:4896
	ds_write_b16 v61, v30 offset:5040
	s_waitcnt vmcnt(13)
	v_lshlrev_b32_e32 v31, 16, v254
	v_mul_f32_e32 v31, 0x3fd744fd, v31
	v_fmac_f32_e32 v31, v24, v253
	s_waitcnt vmcnt(12)
	v_lshlrev_b32_e32 v24, 16, v255
	v_mul_f32_e32 v24, 0x3fd744fd, v24
	v_fmac_f32_e32 v24, v25, v253
	v_cvt_pk_bf16_f32 v24, v24, s0
	ds_write_b16 v61, v24 offset:4784
	s_waitcnt vmcnt(11)
	v_lshlrev_b32_e32 v25, 16, v202
	v_mul_f32_e32 v25, 0x3fd744fd, v25
	v_fmac_f32_e32 v25, v26, v253
	v_cvt_pk_bf16_f32 v24, v25, s0
	ds_write_b16 v61, v24 offset:4928
	s_waitcnt vmcnt(10)
	v_lshlrev_b32_e32 v26, 16, v203
	v_mul_f32_e32 v26, 0x3fd744fd, v26
	v_fmac_f32_e32 v26, v27, v253
	v_cvt_pk_bf16_f32 v27, v31, s0
	v_cvt_pk_bf16_f32 v24, v26, s0
	ds_write_b16 v61, v27 offset:4640
	ds_write_b16 v61, v24 offset:5072
	s_waitcnt vmcnt(8)
	v_lshlrev_b32_e32 v25, 16, v205
	v_mul_f32_e32 v25, 0x3fd744fd, v25
	v_fmac_f32_e32 v25, v20, v204
	s_waitcnt vmcnt(7)
	v_lshlrev_b32_e32 v20, 16, v206
	v_mul_f32_e32 v20, 0x3fd744fd, v20
	v_fmac_f32_e32 v20, v21, v204
	v_cvt_pk_bf16_f32 v20, v20, s0
	ds_write_b16 v61, v20 offset:4816
	s_waitcnt vmcnt(6)
	v_lshlrev_b32_e32 v21, 16, v207
	v_mul_f32_e32 v21, 0x3fd744fd, v21
	v_fmac_f32_e32 v21, v22, v204
	v_cvt_pk_bf16_f32 v20, v21, s0
	ds_write_b16 v61, v20 offset:4960
	s_waitcnt vmcnt(5)
	v_lshlrev_b32_e32 v22, 16, v208
	v_mul_f32_e32 v22, 0x3fd744fd, v22
	v_fmac_f32_e32 v22, v23, v204
	v_cvt_pk_bf16_f32 v23, v25, s0
	v_cvt_pk_bf16_f32 v20, v22, s0
	ds_write_b16 v61, v23 offset:4672
	ds_write_b16 v61, v20 offset:5104
	v_or_b32_e32 v22, 50, v60
	v_ashrrev_i32_e32 v23, 31, v22
	v_lshlrev_b64 v[24:25], 12, v[22:23]
	v_or_b32_e32 v22, 51, v60
	v_ashrrev_i32_e32 v23, 31, v22
	v_lshlrev_b64 v[26:27], 12, v[22:23]
	s_waitcnt vmcnt(3)
	v_lshlrev_b32_e32 v21, 16, v210
	v_mul_f32_e32 v21, 0x3fd744fd, v21
	v_fmac_f32_e32 v21, v16, v209
	s_waitcnt vmcnt(2)
	v_lshlrev_b32_e32 v16, 16, v211
	v_mul_f32_e32 v16, 0x3fd744fd, v16
	v_fmac_f32_e32 v16, v17, v209
	v_cvt_pk_bf16_f32 v16, v16, s0
	ds_write_b16 v61, v16 offset:4848
	s_waitcnt vmcnt(1)
	v_lshlrev_b32_e32 v17, 16, v212
	v_mul_f32_e32 v17, 0x3fd744fd, v17
	v_fmac_f32_e32 v17, v18, v209
	v_cvt_pk_bf16_f32 v16, v17, s0
	ds_write_b16 v61, v16 offset:4992
	v_add_u32_e32 v17, 0xfffff030, v72
	v_lshrrev_b32_e32 v17, 12, v17
	v_add_u32_e32 v17, 1, v17
	s_waitcnt vmcnt(0)
	v_lshlrev_b32_e32 v18, 16, v213
	v_mul_f32_e32 v18, 0x3fd744fd, v18
	v_fmac_f32_e32 v18, v19, v209
	v_cvt_pk_bf16_f32 v16, v18, s0
	ds_write_b16 v61, v16 offset:5136
	v_or_b32_e32 v16, 48, v60
	v_cmp_lt_i32_e32 vcc, s9, v16
	v_cvt_pk_bf16_f32 v19, v21, s0
	ds_write_b16 v61, v19 offset:4704
	v_cndmask_b32_e32 v136, 0, v17, vcc
	v_ashrrev_i32_e32 v17, 31, v16
	v_lshl_add_u64 v[18:19], v[136:137], 0, s[0:1]
	v_lshlrev_b64 v[16:17], 12, v[16:17]
	v_mad_u64_u32 v[20:21], s[6:7], v18, s5, v[64:65]
	v_lshl_add_u64 v[22:23], v[62:63], 0, v[16:17]
	global_load_ushort v214, v[22:23], off
	v_mad_i32_i24 v21, v19, s5, v21
	v_lshl_add_u64 v[20:21], v[20:21], 0, v[66:67]
	global_load_dword v215, v[20:21], off
	v_or_b32_e32 v18, 49, v60
	v_ashrrev_i32_e32 v19, 31, v18
	v_lshlrev_b64 v[18:19], 12, v[18:19]
	s_ashr_i32 s5, s4, 31
	s_lshl_b64 s[4:5], s[4:5], 1
	s_add_u32 s4, s46, s4
	s_addc_u32 s5, s47, s5
	v_lshlrev_b32_e32 v136, 1, v73
	s_add_i32 s8, s8, 1
	s_mov_b64 s[6:7], 0
	s_waitcnt vmcnt(1)
	v_lshlrev_b32_e32 v16, 16, v214
	v_mul_f32_e32 v29, 0x3fd744fd, v16
	v_lshl_add_u64 v[16:17], v[62:63], 0, v[18:19]
	global_load_ushort v216, v[16:17], off
	s_waitcnt vmcnt(1)
	v_fmac_f32_e32 v29, v12, v215
	v_lshl_add_u64 v[18:19], v[62:63], 0, v[24:25]
	global_load_ushort v217, v[18:19], off
	s_waitcnt vmcnt(1)
	v_lshlrev_b32_e32 v12, 16, v216
	v_mul_f32_e32 v30, 0x3fd744fd, v12
	v_fmac_f32_e32 v30, v13, v215
	s_waitcnt vmcnt(0)
	v_lshlrev_b32_e32 v12, 16, v217
	v_mul_f32_e32 v24, 0x3fd744fd, v12
	v_lshl_add_u64 v[12:13], v[62:63], 0, v[26:27]
	global_load_ushort v218, v[12:13], off
	global_load_dword v219, v[20:21], off offset:64
	global_load_ushort v220, v[22:23], off offset:32
	global_load_ushort v221, v[16:17], off offset:32
	global_load_ushort v222, v[18:19], off offset:32
	global_load_ushort v223, v[12:13], off offset:32
	global_load_dword v224, v[20:21], off offset:128
	global_load_ushort v225, v[22:23], off offset:64
	global_load_ushort v226, v[16:17], off offset:64
	global_load_ushort v227, v[18:19], off offset:64
	global_load_ushort v228, v[12:13], off offset:64
	global_load_dword v229, v[20:21], off offset:192
	global_load_ushort v230, v[22:23], off offset:96
	global_load_ushort v231, v[16:17], off offset:96
	global_load_ushort v232, v[18:19], off offset:96
	global_load_ushort v233, v[12:13], off offset:96
	v_fmac_f32_e32 v24, v14, v215
	s_waitcnt vmcnt(15)
	v_lshlrev_b32_e32 v14, 16, v218
	v_mul_f32_e32 v14, 0x3fd744fd, v14
	v_fmac_f32_e32 v14, v15, v215
	v_cvt_pk_bf16_f32 v15, v29, s0
	ds_write_b16 v61, v15 offset:6912
	v_cvt_pk_bf16_f32 v15, v30, s0
	ds_write_b16 v61, v15 offset:7056
	v_cvt_pk_bf16_f32 v15, v24, s0
	v_cvt_pk_bf16_f32 v14, v14, s0
	ds_write_b16 v61, v15 offset:7200
	ds_write_b16 v61, v14 offset:7344
	s_waitcnt vmcnt(13)
	v_lshlrev_b32_e32 v15, 16, v220
	v_mul_f32_e32 v15, 0x3fd744fd, v15
	v_fmac_f32_e32 v15, v8, v219
	s_waitcnt vmcnt(12)
	v_lshlrev_b32_e32 v8, 16, v221
	v_mul_f32_e32 v8, 0x3fd744fd, v8
	v_fmac_f32_e32 v8, v9, v219
	v_cvt_pk_bf16_f32 v8, v8, s0
	ds_write_b16 v61, v8 offset:7088
	s_waitcnt vmcnt(11)
	v_lshlrev_b32_e32 v9, 16, v222
	v_mul_f32_e32 v9, 0x3fd744fd, v9
	v_fmac_f32_e32 v9, v10, v219
	v_cvt_pk_bf16_f32 v8, v9, s0
	ds_write_b16 v61, v8 offset:7232
	s_waitcnt vmcnt(10)
	v_lshlrev_b32_e32 v10, 16, v223
	v_mul_f32_e32 v10, 0x3fd744fd, v10
	v_fmac_f32_e32 v10, v11, v219
	v_cvt_pk_bf16_f32 v11, v15, s0
	v_cvt_pk_bf16_f32 v8, v10, s0
	ds_write_b16 v61, v11 offset:6944
	ds_write_b16 v61, v8 offset:7376
	s_waitcnt vmcnt(8)
	v_lshlrev_b32_e32 v9, 16, v225
	v_mul_f32_e32 v9, 0x3fd744fd, v9
	v_fmac_f32_e32 v9, v4, v224
	s_waitcnt vmcnt(7)
	v_lshlrev_b32_e32 v4, 16, v226
	v_mul_f32_e32 v4, 0x3fd744fd, v4
	v_fmac_f32_e32 v4, v5, v224
	v_cvt_pk_bf16_f32 v4, v4, s0
	ds_write_b16 v61, v4 offset:7120
	s_waitcnt vmcnt(6)
	v_lshlrev_b32_e32 v5, 16, v227
	v_mul_f32_e32 v5, 0x3fd744fd, v5
	v_fmac_f32_e32 v5, v6, v224
	v_cvt_pk_bf16_f32 v4, v5, s0
	ds_write_b16 v61, v4 offset:7264
	s_waitcnt vmcnt(5)
	v_lshlrev_b32_e32 v6, 16, v228
	v_mul_f32_e32 v6, 0x3fd744fd, v6
	v_fmac_f32_e32 v6, v7, v224
	v_cvt_pk_bf16_f32 v7, v9, s0
	v_cvt_pk_bf16_f32 v4, v6, s0
	ds_write_b16 v61, v7 offset:6976
	ds_write_b16 v61, v4 offset:7408
	s_waitcnt vmcnt(3)
	v_lshlrev_b32_e32 v5, 16, v230
	v_mul_f32_e32 v5, 0x3fd744fd, v5
	v_fmac_f32_e32 v5, v0, v229
	s_waitcnt vmcnt(2)
	v_lshlrev_b32_e32 v0, 16, v231
	v_mul_f32_e32 v0, 0x3fd744fd, v0
	v_fmac_f32_e32 v0, v1, v229
	v_cvt_pk_bf16_f32 v0, v0, s0
	ds_write_b16 v61, v0 offset:7152
	s_waitcnt vmcnt(1)
	v_lshlrev_b32_e32 v1, 16, v232
	v_mul_f32_e32 v1, 0x3fd744fd, v1
	v_fmac_f32_e32 v1, v2, v229
	v_cvt_pk_bf16_f32 v0, v1, s0
	ds_write_b16 v61, v0 offset:7296
	v_mov_b32_e32 v1, v137
	s_waitcnt vmcnt(0)
	v_lshlrev_b32_e32 v2, 16, v233
	v_mul_f32_e32 v2, 0x3fd744fd, v2
	v_fmac_f32_e32 v2, v3, v229
	v_cvt_pk_bf16_f32 v0, v2, s0
	ds_write_b16 v61, v0 offset:7440
	v_lshlrev_b32_e32 v0, 4, v71
	v_cvt_pk_bf16_f32 v3, v5, s0
	v_and_b32_e32 v0, 0x70, v0
	ds_write_b16 v61, v3 offset:7008
	v_or_b32_e32 v6, v74, v0
	v_lshl_add_u64 v[2:3], s[4:5], 0, v[136:137]
	s_movk_i32 s4, 0x90
	v_mad_u32_u24 v10, v70, s4, v6
	v_lshl_add_u64 v[4:5], v[2:3], 0, v[0:1]
	ds_read_b128 v[0:3], v10
	v_or_b32_e32 v6, v72, v70
	v_ashrrev_i32_e32 v7, 31, v6
	v_lshlrev_b64 v[8:9], 12, v[6:7]
	v_lshl_add_u64 v[8:9], v[4:5], 0, v[8:9]
	s_waitcnt lgkmcnt(0)
	global_store_dwordx4 v[8:9], v[0:3], off offset:2048
	ds_read_b128 v[0:3], v10 offset:1152
	v_or_b32_e32 v8, 8, v6
	v_ashrrev_i32_e32 v9, 31, v8
	v_lshlrev_b64 v[8:9], 12, v[8:9]
	v_lshl_add_u64 v[8:9], v[4:5], 0, v[8:9]
	s_waitcnt lgkmcnt(0)
	global_store_dwordx4 v[8:9], v[0:3], off offset:2048
	ds_read_b128 v[0:3], v10 offset:2304
	v_or_b32_e32 v8, 16, v6
	v_ashrrev_i32_e32 v9, 31, v8
	v_lshlrev_b64 v[8:9], 12, v[8:9]
	v_lshl_add_u64 v[8:9], v[4:5], 0, v[8:9]
	s_waitcnt lgkmcnt(0)
	global_store_dwordx4 v[8:9], v[0:3], off offset:2048
	ds_read_b128 v[0:3], v10 offset:3456
	v_or_b32_e32 v8, 24, v6
	v_ashrrev_i32_e32 v9, 31, v8
	v_lshlrev_b64 v[8:9], 12, v[8:9]
	v_lshl_add_u64 v[8:9], v[4:5], 0, v[8:9]
	s_waitcnt lgkmcnt(0)
	global_store_dwordx4 v[8:9], v[0:3], off offset:2048
	ds_read_b128 v[0:3], v10 offset:4608
	v_or_b32_e32 v8, 32, v6
	v_ashrrev_i32_e32 v9, 31, v8
	v_lshlrev_b64 v[8:9], 12, v[8:9]
	v_lshl_add_u64 v[8:9], v[4:5], 0, v[8:9]
	s_waitcnt lgkmcnt(0)
	global_store_dwordx4 v[8:9], v[0:3], off offset:2048
	ds_read_b128 v[0:3], v10 offset:5760
	v_or_b32_e32 v8, 40, v6
	v_ashrrev_i32_e32 v9, 31, v8
	v_lshlrev_b64 v[8:9], 12, v[8:9]
	v_lshl_add_u64 v[8:9], v[4:5], 0, v[8:9]
	s_waitcnt lgkmcnt(0)
	global_store_dwordx4 v[8:9], v[0:3], off offset:2048
	ds_read_b128 v[0:3], v10 offset:6912
	v_or_b32_e32 v8, 48, v6
	v_ashrrev_i32_e32 v9, 31, v8
	v_lshlrev_b64 v[8:9], 12, v[8:9]
	v_lshl_add_u64 v[8:9], v[4:5], 0, v[8:9]
	s_waitcnt lgkmcnt(0)
	global_store_dwordx4 v[8:9], v[0:3], off offset:2048
	ds_read_b128 v[0:3], v10 offset:8064
	v_or_b32_e32 v6, 56, v6
	v_ashrrev_i32_e32 v7, 31, v6
	v_lshlrev_b64 v[6:7], 12, v[6:7]
	v_lshl_add_u64 v[4:5], v[4:5], 0, v[6:7]
	s_waitcnt lgkmcnt(0)
	global_store_dwordx4 v[4:5], v[0:3], off offset:2048
	s_barrier
	s_branch .LBB0_162
